# v22
# speedup vs baseline: 1.0058x; 1.0058x over previous
; #define PG8_STAGE(bufoff, gbase, voff) do { const __amdgpu_buffer_rsrc_t _rs = __builtin_amdgcn_make_buffer_rsrc((void*)(gbase), 0, 0x7fffffff, 0x00020000); _Pragma("unroll") for (int _i = 0; _i < 2; ++_i) \
;         __builtin_amdgcn_raw_ptr_buffer_load_lds(_rs, (LAS unsigned*)(lds + (bufoff) + ldsw + _i * 8192), 16, (int)(voff)[_i], 0, 0, 0); } while (0)
; #define PG8_WAIT_V(n) asm volatile("s_waitcnt vmcnt(" #n ")" ::: "memory")
; #define PG8_BAR __builtin_amdgcn_s_barrier()
; template <class Epi, class Sched, bool F8 = false>
; __device__ __forceinline__ void gemm_phase(LAS unsigned char* lds, const int lda, const int ldb, const Sched& S, const Epi& E) {
;     ...
;     PG8_STAGE(PG8_SB(0, 0), cB, voffB); PG8_STAGE(PG8_SB(0, 1), cB + hstepB, voffB); PG8_STAGE(PG8_SA(0, 0), cA, voffA); PG8_STAGE(PG8_SA(0, 1), cA + hstepA, voffA);
;     if (wr == 1) PG8_BAR;
;     PG8_WAIT_V(2); PG8_BAR;
;     PG8_STAGE(PG8_SB(1, 0), cB + kstepB, voffB); PG8_STAGE(PG8_SA(1, 0), cA + kstep, voffA); PG8_STAGE(PG8_SB(1, 1), cB + hstepB + kstepB, voffB);
;     PG8_WAIT_V(6); PG8_BAR;
.LBB0_106:
	s_lshl_b32 s5, s5, 5
	s_and_b32 s86, s5, 0x60
	s_lshl_b32 s85, s4, 6
	s_lshl_b32 s4, s4, 13
	s_lshl_b32 s5, s86, 7
	s_add_u32 s16, s22, 0x8000
	s_addc_u32 s7, s23, 0
	s_add_i32 s87, s3, 0x18000
	s_and_b32 s17, s7, 0xffff
	s_mov_b32 m0, s87
	s_add_i32 s88, s3, 0x1a000
	buffer_load_dwordx4 v137, s[16:19], 0 offen lds
	s_mov_b32 m0, s88
	v_and_b32_e32 v1, 48, v0
	buffer_load_dwordx4 v139, s[16:19], 0 offen lds
	s_add_u32 s16, s20, 0x80
	s_addc_u32 s7, s21, 0
	s_add_i32 s89, s3, 0x8000
	s_and_b32 s17, s7, 0xffff
	s_mov_b32 m0, s89
	s_add_i32 s90, s3, 0xa000
	buffer_load_dwordx4 v136, s[16:19], 0 offen lds
	s_mov_b32 m0, s90
	v_lshlrev_b32_e32 v2, 6, v0
	buffer_load_dwordx4 v138, s[16:19], 0 offen lds
	s_add_u32 s16, s22, 0xc000
	s_addc_u32 s7, s23, 0
	s_add_i32 s91, s3, 0x1c000
	s_and_b32 s17, s7, 0xffff
	s_mov_b32 m0, s91
	s_add_i32 s92, s3, 0x1e000
	buffer_load_dwordx4 v137, s[16:19], 0 offen lds
	s_mov_b32 m0, s92
	s_movk_i32 s7, 0x3c0
	buffer_load_dwordx4 v139, s[16:19], 0 offen lds
	v_lshlrev_b32_e32 v0, 2, v0
	v_and_or_b32 v1, v2, s7, v1
	v_and_b32_e32 v0, 32, v0
	v_bitop3_b32 v2, v1, s4, v0 bitop3:0xde
	v_bitop3_b32 v0, s5, v1, v0 bitop3:0xf6
	s_waitcnt vmcnt(8)
	s_barrier
	s_waitcnt vmcnt(6)
	s_barrier
	s_load_dwordx2 s[4:5], s[0:1], 0xe8
	s_add_i32 s93, s3, 0xc000
	s_cmpk_lt_u32 s24, 0x100
	v_add_u32_e32 v0, 0, v0
	s_cselect_b64 s[38:39], -1, 0
	s_add_i32 s94, s3, 0xe000
	s_waitcnt lgkmcnt(0)
	s_ashr_i32 s95, s4, 31
	s_mov_b32 s96, s4
	s_ashr_i32 s97, s2, 31
	v_mov_b64_e32 v[128:129], 0x200
	v_mov_b64_e32 v[130:131], 0x1ff
	v_add_u32_e32 v140, 0x10000, v0
	v_add_u32_e32 v141, 0x14000, v0
	v_add_u32_e32 v142, 0, v2
	v_add_u32_e32 v143, 0x18000, v0
	v_add_u32_e32 v144, 0x1c000, v0
	s_mov_b64 s[70:71], s[20:21]
	s_mov_b64 s[72:73], s[22:23]
	s_branch .LBB0_109

; #define PG8_STAGE(bufoff, gbase, voff) do { const __amdgpu_buffer_rsrc_t _rs = __builtin_amdgcn_make_buffer_rsrc((void*)(gbase), 0, 0x7fffffff, 0x00020000); _Pragma("unroll") for (int _i = 0; _i < 2; ++_i) \
;         __builtin_amdgcn_raw_ptr_buffer_load_lds(_rs, (LAS unsigned*)(lds + (bufoff) + ldsw + _i * 8192), 16, (int)(voff)[_i], 0, 0, 0); } while (0)
; #define PG8_WAIT_V(n) asm volatile("s_waitcnt vmcnt(" #n ")" ::: "memory")
; #define PG8_BAR __builtin_amdgcn_s_barrier()
; template <class Epi, class Sched, bool F8 = false>
; __device__ __forceinline__ void gemm_phase(LAS unsigned char* lds, const int lda, const int ldb, const Sched& S, const Epi& E) {
;     ...
;     PG8_STAGE(PG8_SB(0, 0), cB, voffB); PG8_STAGE(PG8_SB(0, 1), cB + hstepB, voffB); PG8_STAGE(PG8_SA(0, 0), cA, voffA); PG8_STAGE(PG8_SA(0, 1), cA + hstepA, voffA);
;     if (wr == 1) PG8_BAR;
;     PG8_WAIT_V(2); PG8_BAR;
;     PG8_STAGE(PG8_SB(1, 0), cB + kstepB, voffB); PG8_STAGE(PG8_SA(1, 0), cA + kstep, voffA); PG8_STAGE(PG8_SB(1, 1), cB + hstepB + kstepB, voffB);
;     PG8_WAIT_V(6); PG8_BAR;
.LBB0_164:
	s_lshl_b32 s5, s5, 5
	s_and_b32 s89, s5, 0x60
	s_lshl_b32 s88, s4, 6
	s_lshl_b32 s4, s4, 13
	s_lshl_b32 s5, s89, 7
	s_add_u32 s16, s22, 0x8000
	s_addc_u32 s7, s23, 0
	s_add_i32 s90, s76, 0x18000
	s_and_b32 s17, s7, 0xffff
	s_mov_b32 m0, s90
	s_add_i32 s91, s76, 0x1a000
	buffer_load_dwordx4 v137, s[16:19], 0 offen lds
	s_mov_b32 m0, s91
	v_and_b32_e32 v1, 48, v0
	buffer_load_dwordx4 v139, s[16:19], 0 offen lds
	s_add_u32 s16, s20, 0x80
	s_addc_u32 s7, s21, 0
	s_add_i32 s92, s76, 0x8000
	s_and_b32 s17, s7, 0xffff
	s_mov_b32 m0, s92
	s_add_i32 s93, s76, 0xa000
	buffer_load_dwordx4 v136, s[16:19], 0 offen lds
	s_mov_b32 m0, s93
	v_lshlrev_b32_e32 v2, 6, v0
	buffer_load_dwordx4 v138, s[16:19], 0 offen lds
	s_add_u32 s16, s22, 0xc000
	s_addc_u32 s7, s23, 0
	s_add_i32 s94, s76, 0x1c000
	s_and_b32 s17, s7, 0xffff
	s_mov_b32 m0, s94
	s_add_i32 s95, s76, 0x1e000
	buffer_load_dwordx4 v137, s[16:19], 0 offen lds
	s_mov_b32 m0, s95
	s_movk_i32 s7, 0x3c0
	buffer_load_dwordx4 v139, s[16:19], 0 offen lds
	v_lshlrev_b32_e32 v0, 2, v0
	v_and_or_b32 v1, v2, s7, v1
	v_and_b32_e32 v0, 32, v0
	v_bitop3_b32 v2, v1, s4, v0 bitop3:0xde
	v_bitop3_b32 v0, s5, v1, v0 bitop3:0xf6
	s_waitcnt vmcnt(8)
	s_barrier
	s_waitcnt vmcnt(6)
	s_barrier
	s_load_dwordx2 s[4:5], s[0:1], 0xe8
	s_waitcnt lgkmcnt(0)
	s_add_i32 s96, s76, 0xc000
	s_cmpk_lt_u32 s3, 0x100
	v_add_u32_e32 v0, 0, v0
	s_cselect_b64 s[38:39], -1, 0
	s_add_i32 s97, s76, 0xe000
	s_ashr_i32 s3, s4, 31
	s_mov_b32 s8, s4
	s_ashr_i32 s9, s2, 31
	v_mov_b64_e32 v[128:129], 0x400
	v_mov_b64_e32 v[130:131], 0x3ff
	v_add_u32_e32 v140, 0x10000, v0
	v_add_u32_e32 v141, 0x14000, v0
	v_add_u32_e32 v142, 0, v2
	v_mov_b32_e32 v143, 0x7f7f7f7f
	v_add_u32_e32 v144, 0x18000, v0
	v_add_u32_e32 v145, 0x1c000, v0
	s_mov_b64 s[70:71], s[20:21]
	s_mov_b64 s[72:73], s[22:23]
	s_branch .LBB0_167

; #define PG8_STAGE(bufoff, gbase, voff) do { const __amdgpu_buffer_rsrc_t _rs = __builtin_amdgcn_make_buffer_rsrc((void*)(gbase), 0, 0x7fffffff, 0x00020000); _Pragma("unroll") for (int _i = 0; _i < 2; ++_i) \
;         __builtin_amdgcn_raw_ptr_buffer_load_lds(_rs, (LAS unsigned*)(lds + (bufoff) + ldsw + _i * 8192), 16, (int)(voff)[_i], 0, 0, 0); } while (0)
; #define PG8_WAIT_V(n) asm volatile("s_waitcnt vmcnt(" #n ")" ::: "memory")
; #define PG8_BAR __builtin_amdgcn_s_barrier()
; template <class Epi, class Sched, bool F8 = false>
; __device__ __forceinline__ void gemm_phase(LAS unsigned char* lds, const int lda, const int ldb, const Sched& S, const Epi& E) {
;     ...
;     PG8_STAGE(PG8_SB(0, 0), cB, voffB); PG8_STAGE(PG8_SB(0, 1), cB + hstepB, voffB); PG8_STAGE(PG8_SA(0, 0), cA, voffA); PG8_STAGE(PG8_SA(0, 1), cA + hstepA, voffA);
;     if (wr == 1) PG8_BAR;
;     PG8_WAIT_V(2); PG8_BAR;
;     PG8_STAGE(PG8_SB(1, 0), cB + kstepB, voffB); PG8_STAGE(PG8_SA(1, 0), cA + kstep, voffA); PG8_STAGE(PG8_SB(1, 1), cB + hstepB + kstepB, voffB);
;     PG8_WAIT_V(6); PG8_BAR;
.LBB0_397:
	s_ashr_i32 s33, s2, 8
	s_add_u32 s26, s58, 0x2f114000
	s_addc_u32 s27, s59, 0
	s_add_u32 s46, s58, 0x31114000
	s_addc_u32 s47, s59, 0
	s_lshl_b32 s1, s37, 5
	s_and_b32 s85, s1, 0x60
	s_lshl_b32 s84, s36, 6
	s_lshl_b32 s0, s36, 13
	s_lshl_b32 s1, s85, 7
	s_add_u32 s4, s18, 0x8000
	s_addc_u32 s5, s19, 0
	s_add_i32 s86, s74, 0x18000
	s_and_b32 s5, s5, 0xffff
	s_mov_b32 m0, s86
	s_add_i32 s87, s74, 0x1a000
	buffer_load_dwordx4 v177, s[4:7], 0 offen lds
	s_mov_b32 m0, s87
	v_and_b32_e32 v1, 48, v0
	buffer_load_dwordx4 v179, s[4:7], 0 offen lds
	s_add_u32 s4, s16, 0x80
	s_addc_u32 s5, s17, 0
	s_add_i32 s88, s74, 0x8000
	s_and_b32 s5, s5, 0xffff
	s_mov_b32 m0, s88
	s_add_i32 s89, s74, 0xa000
	buffer_load_dwordx4 v176, s[4:7], 0 offen lds
	s_mov_b32 m0, s89
	v_lshlrev_b32_e32 v2, 6, v0
	buffer_load_dwordx4 v178, s[4:7], 0 offen lds
	s_add_u32 s4, s18, 0xc000
	s_addc_u32 s5, s19, 0
	s_add_i32 s90, s74, 0x1c000
	s_and_b32 s5, s5, 0xffff
	s_mov_b32 m0, s90
	s_add_i32 s91, s74, 0x1e000
	buffer_load_dwordx4 v177, s[4:7], 0 offen lds
	s_mov_b32 m0, s91
	v_lshlrev_b32_e32 v0, 2, v0
	buffer_load_dwordx4 v179, s[4:7], 0 offen lds
	s_movk_i32 s4, 0x3c0
	v_and_or_b32 v1, v2, s4, v1
	v_and_b32_e32 v0, 32, v0
	v_bitop3_b32 v2, v1, s0, v0 bitop3:0xde
	v_bitop3_b32 v0, s1, v1, v0 bitop3:0xf6
	s_waitcnt vmcnt(8)
	s_barrier
	s_waitcnt vmcnt(6)
	s_add_i32 s92, s74, 0xc000
	s_cmpk_lt_u32 s35, 0x100
	v_readlane_b32 s0, v255, 0
	v_add_u32_e32 v0, 0, v0
	s_cselect_b64 s[66:67], -1, 0
	s_add_i32 s93, s74, 0xe000
	s_ashr_i32 s94, s0, 31
	s_mov_b32 s95, s0
	s_ashr_i32 s96, s2, 31
	v_mov_b64_e32 v[144:145], 0x200
	v_mov_b64_e32 v[146:147], 0x1ff
	v_add_u32_e32 v180, 0x10000, v0
	v_add_u32_e32 v181, 0x14000, v0
	v_add_u32_e32 v182, 0, v2
	v_add_u32_e32 v183, 0x18000, v0
	v_add_u32_e32 v184, 0x1c000, v0
	s_mov_b64 s[70:71], s[16:17]
	s_mov_b64 s[72:73], s[18:19]
	s_barrier
	v_readlane_b32 s1, v255, 1
	s_branch .LBB0_400

; #define PG8_STAGE(bufoff, gbase, voff) do { const __amdgpu_buffer_rsrc_t _rs = __builtin_amdgcn_make_buffer_rsrc((void*)(gbase), 0, 0x7fffffff, 0x00020000); _Pragma("unroll") for (int _i = 0; _i < 2; ++_i) \
;         __builtin_amdgcn_raw_ptr_buffer_load_lds(_rs, (LAS unsigned*)(lds + (bufoff) + ldsw + _i * 8192), 16, (int)(voff)[_i], 0, 0, 0); } while (0)
; #define PG8_WAIT_V(n) asm volatile("s_waitcnt vmcnt(" #n ")" ::: "memory")
; #define PG8_BAR __builtin_amdgcn_s_barrier()
; template <class Epi, class Sched, bool F8 = false>
; __device__ __forceinline__ void gemm_phase(LAS unsigned char* lds, const int lda, const int ldb, const Sched& S, const Epi& E) {
;     ...
;     f32x4 acc[2][2][4][2];
; #pragma unroll
;     for (int a = 0; a < 2; ++a)
; #pragma unroll
;         for (int b = 0; b < 2; ++b)
; #pragma unroll
;             for (int m = 0; m < 4; ++m)
; #pragma unroll
;                 for (int n = 0; n < 2; ++n) acc[a][b][m][n] = (f32x4){0.f, 0.f, 0.f, 0.f};
;     ...
;     PG8_STAGE(PG8_SB(0, 0), cB, voffB); PG8_STAGE(PG8_SB(0, 1), cB + hstepB, voffB); PG8_STAGE(PG8_SA(0, 0), cA, voffA); PG8_STAGE(PG8_SA(0, 1), cA + hstepA, voffA);
;     if (wr == 1) PG8_BAR;
;     PG8_WAIT_V(2); PG8_BAR;
;     PG8_STAGE(PG8_SB(1, 0), cB + kstepB, voffB); PG8_STAGE(PG8_SA(1, 0), cA + kstep, voffA); PG8_STAGE(PG8_SB(1, 1), cB + hstepB + kstepB, voffB);
;     PG8_WAIT_V(6); PG8_BAR;
.LBB0_479:
	s_add_u32 s79, s58, 0x31114000
	s_addc_u32 s80, s59, 0
	s_add_u32 s81, s58, 0x7f14000
	s_addc_u32 s82, s59, 0
	s_add_u32 s20, s58, 0x1f114000
	s_addc_u32 s21, s59, 0
	s_add_u32 s26, s58, 0x1b114000
	v_and_b32_e32 v1, 48, v0
	v_lshlrev_b32_e32 v2, 6, v0
	s_movk_i32 s4, 0x3c0
	v_lshlrev_b32_e32 v0, 2, v0
	s_addc_u32 s27, s59, 0
	s_lshl_b32 s83, s0, 6
	s_lshl_b32 s0, s0, 13
	v_and_or_b32 v1, v2, s4, v1
	v_and_b32_e32 v0, 32, v0
	v_bitop3_b32 v2, v1, s0, v0 bitop3:0xde
	s_lshl_b32 s0, s1, 5
	s_and_b32 s84, s0, 0x60
	s_lshl_b32 s0, s84, 7
	s_add_u32 s4, s18, 0x8000
	v_bitop3_b32 v1, s0, v1, v0 bitop3:0xf6
	s_addc_u32 s0, s19, 0
	s_add_i32 s85, s67, 0x18000
	s_and_b32 s5, s0, 0xffff
	s_mov_b32 m0, s85
	s_add_i32 s86, s67, 0x1a000
	buffer_load_dwordx4 v149, s[4:7], 0 offen lds
	s_mov_b32 m0, s86
	v_mov_b32_e32 v0, 0
	buffer_load_dwordx4 v151, s[4:7], 0 offen lds
	s_add_u32 s4, s16, 0x80
	s_addc_u32 s0, s17, 0
	s_add_i32 s87, s67, 0x8000
	s_and_b32 s5, s0, 0xffff
	s_mov_b32 m0, s87
	s_add_i32 s88, s67, 0xa000
	buffer_load_dwordx4 v148, s[4:7], 0 offen lds
	s_mov_b32 m0, s88
	v_mov_b64_e32 v[128:129], 0x200
	buffer_load_dwordx4 v150, s[4:7], 0 offen lds
	s_add_u32 s4, s18, 0xc000
	s_addc_u32 s0, s19, 0
	s_add_i32 s89, s67, 0x1c000
	s_and_b32 s5, s0, 0xffff
	s_mov_b32 m0, s89
	s_add_i32 s90, s67, 0x1e000
	buffer_load_dwordx4 v149, s[4:7], 0 offen lds
	s_mov_b32 m0, s90
	s_add_i32 s91, s67, 0xc000
	buffer_load_dwordx4 v151, s[4:7], 0 offen lds
	s_waitcnt vmcnt(8)
	s_barrier
	s_waitcnt vmcnt(6)
	s_cmpk_lt_u32 s9, 0x100
	s_cselect_b64 s[44:45], -1, 0
	s_add_i32 s92, s67, 0xe000
	s_ashr_i32 s93, s2, 31
	v_mov_b64_e32 v[130:131], 0x1ff
	v_add_u32_e32 v152, 0, v1
	v_add_u32_e32 v153, 0, v2
	s_mov_b32 s95, 0
	v_mov_b32_e32 v1, v0
	v_mov_b32_e32 v2, v0
	v_mov_b32_e32 v3, v0
	v_mov_b32_e32 v4, v0
	v_mov_b32_e32 v5, v0
	v_mov_b32_e32 v6, v0
	v_mov_b32_e32 v7, v0
	v_mov_b32_e32 v8, v0
	v_mov_b32_e32 v9, v0
	v_mov_b32_e32 v10, v0
	v_mov_b32_e32 v11, v0
	v_mov_b32_e32 v12, v0
	v_mov_b32_e32 v13, v0
	v_mov_b32_e32 v14, v0
	v_mov_b32_e32 v15, v0
	v_mov_b32_e32 v16, v0
	v_mov_b32_e32 v17, v0
	v_mov_b32_e32 v18, v0
	v_mov_b32_e32 v19, v0
	v_mov_b32_e32 v20, v0
	v_mov_b32_e32 v21, v0
	v_mov_b32_e32 v22, v0
	v_mov_b32_e32 v23, v0
	v_mov_b32_e32 v24, v0
	v_mov_b32_e32 v25, v0
	v_mov_b32_e32 v26, v0
	v_mov_b32_e32 v27, v0
	v_mov_b32_e32 v28, v0
	v_mov_b32_e32 v29, v0
	v_mov_b32_e32 v30, v0
	v_mov_b32_e32 v31, v0
	v_mov_b32_e32 v32, v0
	v_mov_b32_e32 v33, v0
	v_mov_b32_e32 v34, v0
	v_mov_b32_e32 v35, v0
	v_mov_b32_e32 v36, v0
	v_mov_b32_e32 v37, v0
	v_mov_b32_e32 v38, v0
	v_mov_b32_e32 v39, v0
	v_mov_b32_e32 v40, v0
	v_mov_b32_e32 v41, v0
	v_mov_b32_e32 v42, v0
	v_mov_b32_e32 v43, v0
	v_mov_b32_e32 v44, v0
	v_mov_b32_e32 v45, v0
	v_mov_b32_e32 v46, v0
	v_mov_b32_e32 v47, v0
	v_mov_b32_e32 v48, v0
	v_mov_b32_e32 v49, v0
	v_mov_b32_e32 v50, v0
	v_mov_b32_e32 v51, v0
	v_mov_b32_e32 v52, v0
	v_mov_b32_e32 v53, v0
	v_mov_b32_e32 v54, v0
	v_mov_b32_e32 v55, v0
	v_mov_b32_e32 v56, v0
	v_mov_b32_e32 v57, v0
	v_mov_b32_e32 v58, v0
	v_mov_b32_e32 v59, v0
	v_mov_b32_e32 v60, v0
	v_mov_b32_e32 v61, v0
	v_mov_b32_e32 v62, v0
	v_mov_b32_e32 v63, v0
	v_mov_b32_e32 v64, v0
	v_mov_b32_e32 v65, v0
	v_mov_b32_e32 v66, v0
	v_mov_b32_e32 v67, v0
	v_mov_b32_e32 v68, v0
	v_mov_b32_e32 v69, v0
	v_mov_b32_e32 v70, v0
	v_mov_b32_e32 v71, v0
	v_mov_b32_e32 v72, v0
	v_mov_b32_e32 v73, v0
	v_mov_b32_e32 v74, v0
	v_mov_b32_e32 v75, v0
	v_mov_b32_e32 v76, v0
	v_mov_b32_e32 v77, v0
	v_mov_b32_e32 v78, v0
	v_mov_b32_e32 v79, v0
	v_mov_b32_e32 v80, v0
	v_mov_b32_e32 v81, v0
	v_mov_b32_e32 v82, v0
	v_mov_b32_e32 v83, v0
	v_mov_b32_e32 v84, v0
	v_mov_b32_e32 v85, v0
	v_mov_b32_e32 v86, v0
	v_mov_b32_e32 v87, v0
	v_mov_b32_e32 v88, v0
	v_mov_b32_e32 v89, v0
	v_mov_b32_e32 v90, v0
	v_mov_b32_e32 v91, v0
	v_mov_b32_e32 v92, v0
	v_mov_b32_e32 v93, v0
	v_mov_b32_e32 v94, v0
	v_mov_b32_e32 v95, v0
	v_mov_b32_e32 v96, v0
	v_mov_b32_e32 v97, v0
	v_mov_b32_e32 v98, v0
	v_mov_b32_e32 v99, v0
	v_mov_b32_e32 v100, v0
	v_mov_b32_e32 v101, v0
	v_mov_b32_e32 v102, v0
	v_mov_b32_e32 v103, v0
	v_mov_b32_e32 v104, v0
	v_mov_b32_e32 v105, v0
	v_mov_b32_e32 v106, v0
	v_mov_b32_e32 v107, v0
	v_mov_b32_e32 v108, v0
	v_mov_b32_e32 v109, v0
	v_mov_b32_e32 v110, v0
	v_mov_b32_e32 v111, v0
	v_mov_b32_e32 v112, v0
	v_mov_b32_e32 v113, v0
	v_mov_b32_e32 v114, v0
	v_mov_b32_e32 v115, v0
	v_mov_b32_e32 v116, v0
	v_mov_b32_e32 v117, v0
	v_mov_b32_e32 v118, v0
	v_mov_b32_e32 v119, v0
	v_mov_b32_e32 v120, v0
	v_mov_b32_e32 v121, v0
	v_mov_b32_e32 v122, v0
	v_mov_b32_e32 v123, v0
	v_mov_b32_e32 v124, v0
	v_mov_b32_e32 v125, v0
	v_mov_b32_e32 v126, v0
	v_mov_b32_e32 v127, v0
	s_mov_b64 s[50:51], s[18:19]
	s_mov_b64 s[48:49], s[16:17]
	s_barrier
	s_branch .LBB0_482

; #define PG8_STAGE(bufoff, gbase, voff) do { const __amdgpu_buffer_rsrc_t _rs = __builtin_amdgcn_make_buffer_rsrc((void*)(gbase), 0, 0x7fffffff, 0x00020000); _Pragma("unroll") for (int _i = 0; _i < 2; ++_i) \
;         __builtin_amdgcn_raw_ptr_buffer_load_lds(_rs, (LAS unsigned*)(lds + (bufoff) + ldsw + _i * 8192), 16, (int)(voff)[_i], 0, 0, 0); } while (0)
; #define PG8_WAIT_V(n) asm volatile("s_waitcnt vmcnt(" #n ")" ::: "memory")
; #define PG8_BAR __builtin_amdgcn_s_barrier()
; template <class Epi, class Sched, bool F8 = false>
; __device__ __forceinline__ void gemm_phase(LAS unsigned char* lds, const int lda, const int ldb, const Sched& S, const Epi& E) {
;     ...
;     PG8_STAGE(PG8_SB(0, 0), cB, voffB); PG8_STAGE(PG8_SB(0, 1), cB + hstepB, voffB); PG8_STAGE(PG8_SA(0, 0), cA, voffA); PG8_STAGE(PG8_SA(0, 1), cA + hstepA, voffA);
;     if (wr == 1) PG8_BAR;
;     PG8_WAIT_V(2); PG8_BAR;
;     PG8_STAGE(PG8_SB(1, 0), cB + kstepB, voffB); PG8_STAGE(PG8_SA(1, 0), cA + kstep, voffA); PG8_STAGE(PG8_SB(1, 1), cB + hstepB + kstepB, voffB);
;     PG8_WAIT_V(6); PG8_BAR;
.LBB0_622:
	s_add_u32 s20, s58, 0x1f114000
	s_addc_u32 s21, s59, 0
	s_add_u32 s81, s58, 0x114000
	s_addc_u32 s82, s59, 0
	s_and_b32 s83, s0, 3
	s_lshl_b32 s84, s1, 6
	s_lshl_b32 s0, s1, 13
	s_lshl_b32 s85, s83, 5
	s_lshl_b32 s1, s83, 12
	s_add_u32 s4, s18, 0x8000
	s_addc_u32 s5, s19, 0
	s_add_i32 s86, s61, 0x18000
	s_and_b32 s5, s5, 0xffff
	s_mov_b32 m0, s86
	s_add_i32 s87, s61, 0x1a000
	buffer_load_dwordx4 v139, s[4:7], 0 offen lds
	s_mov_b32 m0, s87
	v_and_b32_e32 v1, 48, v0
	buffer_load_dwordx4 v141, s[4:7], 0 offen lds
	s_add_u32 s4, s16, 0x80
	s_addc_u32 s5, s17, 0
	s_add_i32 s88, s61, 0x8000
	s_and_b32 s5, s5, 0xffff
	s_mov_b32 m0, s88
	s_add_i32 s89, s61, 0xa000
	buffer_load_dwordx4 v138, s[4:7], 0 offen lds
	s_mov_b32 m0, s89
	v_lshlrev_b32_e32 v2, 6, v0
	buffer_load_dwordx4 v140, s[4:7], 0 offen lds
	s_add_u32 s4, s18, 0xc000
	s_addc_u32 s5, s19, 0
	s_add_i32 s90, s61, 0x1c000
	s_and_b32 s5, s5, 0xffff
	s_mov_b32 m0, s90
	s_add_i32 s91, s61, 0x1e000
	buffer_load_dwordx4 v139, s[4:7], 0 offen lds
	s_mov_b32 m0, s91
	v_lshlrev_b32_e32 v0, 2, v0
	buffer_load_dwordx4 v141, s[4:7], 0 offen lds
	s_movk_i32 s4, 0x3c0
	v_and_or_b32 v1, v2, s4, v1
	v_and_b32_e32 v0, 32, v0
	v_bitop3_b32 v2, v1, s0, v0 bitop3:0xde
	v_bitop3_b32 v0, v1, s1, v0 bitop3:0xde
	s_waitcnt vmcnt(8)
	s_barrier
	s_waitcnt vmcnt(6)
	s_add_i32 s92, s61, 0xc000
	v_add_u32_e32 v0, 0, v0
	s_cmpk_lt_u32 s26, 0x100
	v_readlane_b32 s0, v255, 0
	v_add_u32_e32 v142, 0x10000, v0
	v_add_u32_e32 v143, 0x14000, v0
	v_add_u32_e32 v145, 0x18000, v0
	v_add_u32_e32 v146, 0x1c000, v0
	v_mbcnt_lo_u32_b32 v0, -1, 0
	s_cselect_b64 s[26:27], -1, 0
	s_add_i32 s93, s61, 0xe000
	s_ashr_i32 s94, s0, 31
	s_mov_b32 s95, s0
	s_ashr_i32 s96, s2, 31
	v_mov_b64_e32 v[128:129], 0x200
	v_mov_b64_e32 v[130:131], 0x1ff
	v_add_u32_e32 v144, 0, v2
	v_mbcnt_hi_u32_b32 v147, -1, v0
	s_mov_b64 s[44:45], 0x120000
	s_mov_b32 s97, 0x120000
	s_mov_b64 s[46:47], 0x140000
	s_mov_b32 s33, 0x140000
	s_mov_b64 s[48:49], 0x160000
	s_mov_b32 s62, 0x160000
	s_mov_b64 s[68:69], s[16:17]
	s_mov_b64 s[70:71], s[18:19]
	s_barrier
	v_readlane_b32 s1, v255, 1
	s_branch .LBB0_625

; #define PG8_STAGE(bufoff, gbase, voff) do { const __amdgpu_buffer_rsrc_t _rs = __builtin_amdgcn_make_buffer_rsrc((void*)(gbase), 0, 0x7fffffff, 0x00020000); _Pragma("unroll") for (int _i = 0; _i < 2; ++_i) \
;         __builtin_amdgcn_raw_ptr_buffer_load_lds(_rs, (LAS unsigned*)(lds + (bufoff) + ldsw + _i * 8192), 16, (int)(voff)[_i], 0, 0, 0); } while (0)
; #define PG8_WAIT_V(n) asm volatile("s_waitcnt vmcnt(" #n ")" ::: "memory")
; #define PG8_BAR __builtin_amdgcn_s_barrier()
; template <class Epi, class Sched, bool F8 = false>
; __device__ __forceinline__ void gemm_phase(LAS unsigned char* lds, const int lda, const int ldb, const Sched& S, const Epi& E) {
;     ...
;     PG8_STAGE(PG8_SB(0, 0), cB, voffB); PG8_STAGE(PG8_SB(0, 1), cB + hstepB, voffB); PG8_STAGE(PG8_SA(0, 0), cA, voffA); PG8_STAGE(PG8_SA(0, 1), cA + hstepA, voffA);
;     if (wr == 1) PG8_BAR;
;     PG8_WAIT_V(2); PG8_BAR;
;     PG8_STAGE(PG8_SB(1, 0), cB + kstepB, voffB); PG8_STAGE(PG8_SA(1, 0), cA + kstep, voffA); PG8_STAGE(PG8_SB(1, 1), cB + hstepB + kstepB, voffB);
;     PG8_WAIT_V(6); PG8_BAR;
.LBB0_772:
	s_add_u32 s36, s58, 0x1f114000
	s_addc_u32 s37, s59, 0
	s_add_u32 s38, s58, 0x3b114000
	s_addc_u32 s39, s59, 0
	s_and_b32 s0, s0, 3
	s_lshl_b32 s76, s1, 6
	s_lshl_b32 s16, s1, 13
	s_lshl_b32 s77, s0, 5
	s_lshl_b32 s17, s0, 12
	s_add_u32 s12, s6, 0x8000
	s_addc_u32 s13, s7, 0
	s_add_i32 s78, s51, 0x18000
	s_and_b32 s13, s13, 0xffff
	s_mov_b32 m0, s78
	s_add_i32 s79, s51, 0x1a000
	buffer_load_dwordx4 v177, s[12:15], 0 offen lds
	s_mov_b32 m0, s79
	v_and_b32_e32 v1, 48, v0
	buffer_load_dwordx4 v193, s[12:15], 0 offen lds
	s_add_u32 s12, s4, 0x80
	s_addc_u32 s13, s5, 0
	s_add_i32 s80, s51, 0x8000
	s_and_b32 s13, s13, 0xffff
	s_mov_b32 m0, s80
	s_add_i32 s81, s51, 0xa000
	buffer_load_dwordx4 v175, s[12:15], 0 offen lds
	s_mov_b32 m0, s81
	v_lshlrev_b32_e32 v2, 6, v0
	buffer_load_dwordx4 v179, s[12:15], 0 offen lds
	s_add_u32 s12, s6, 0xc000
	s_addc_u32 s13, s7, 0
	s_add_i32 s82, s51, 0x1c000
	s_and_b32 s13, s13, 0xffff
	s_mov_b32 m0, s82
	s_add_i32 s83, s51, 0x1e000
	buffer_load_dwordx4 v177, s[12:15], 0 offen lds
	s_mov_b32 m0, s83
	s_add_i32 s84, s51, 0xc000
	buffer_load_dwordx4 v193, s[12:15], 0 offen lds
	s_movk_i32 s12, 0x3c0
	v_lshlrev_b32_e32 v0, 2, v0
	s_cmpk_lt_u32 s8, 0x100
	v_and_or_b32 v1, v2, s12, v1
	v_and_b32_e32 v0, 32, v0
	s_cselect_b64 s[40:41], -1, 0
	s_lshl_b32 s1, s1, 5
	s_lshl_b32 s8, s0, 3
	v_bitop3_b32 v2, v1, s16, v0 bitop3:0xde
	v_bitop3_b32 v0, v1, s17, v0 bitop3:0xde
	s_waitcnt vmcnt(8)
	s_barrier
	s_waitcnt vmcnt(6)
	s_or_b32 s85, s8, s1
	s_lshl_b32 s1, s0, 9
	s_or_b32 s0, s9, s0
	s_lshl_b32 s0, s0, 9
	v_readlane_b32 s8, v255, 0
	s_add_i32 s91, 0, 0x20000
	v_add_u32_e32 v0, 0, v0
	s_add_i32 s86, s51, 0xe000
	s_ashr_i32 s87, s8, 31
	s_mov_b32 s88, s8
	s_ashr_i32 s89, s2, 31
	s_add_i32 s90, s91, s1
	s_add_i32 s91, s91, s0
	v_mov_b64_e32 v[180:181], 0xac0
	v_mov_b64_e32 v[182:183], 0xabf
	s_movk_i32 s92, 0x159
	v_add_u32_e32 v194, 0x10000, v0
	v_add_u32_e32 v195, 0x14000, v0
	v_add_u32_e32 v196, 0, v2
	v_add_u32_e32 v197, 0x18000, v0
	v_add_u32_e32 v198, 0x1c000, v0
	s_mov_b32 s93, 0x15800
	v_mov_b32_e32 v185, 0
	s_movk_i32 s94, 0x5600
	s_mov_b64 s[48:49], s[6:7]
	s_mov_b64 s[46:47], s[4:5]
	s_barrier
	v_readlane_b32 s9, v255, 1
	s_branch .LBB0_775

; #define PG8_STAGE(bufoff, gbase, voff) do { const __amdgpu_buffer_rsrc_t _rs = __builtin_amdgcn_make_buffer_rsrc((void*)(gbase), 0, 0x7fffffff, 0x00020000); _Pragma("unroll") for (int _i = 0; _i < 2; ++_i) \
;         __builtin_amdgcn_raw_ptr_buffer_load_lds(_rs, (LAS unsigned*)(lds + (bufoff) + ldsw + _i * 8192), 16, (int)(voff)[_i], 0, 0, 0); } while (0)
; #define PG8_WAIT_V(n) asm volatile("s_waitcnt vmcnt(" #n ")" ::: "memory")
; #define PG8_BAR __builtin_amdgcn_s_barrier()
; template <class Epi, class Sched, bool F8 = false>
; __device__ __forceinline__ void gemm_phase(LAS unsigned char* lds, const int lda, const int ldb, const Sched& S, const Epi& E) {
;     ...
;     PG8_STAGE(PG8_SB(0, 0), cB, voffB); PG8_STAGE(PG8_SB(0, 1), cB + hstepB, voffB); PG8_STAGE(PG8_SA(0, 0), cA, voffA); PG8_STAGE(PG8_SA(0, 1), cA + hstepA, voffA);
;     if (wr == 1) PG8_BAR;
;     PG8_WAIT_V(2); PG8_BAR;
;     PG8_STAGE(PG8_SB(1, 0), cB + kstepB, voffB); PG8_STAGE(PG8_SA(1, 0), cA + kstep, voffA); PG8_STAGE(PG8_SB(1, 1), cB + hstepB + kstepB, voffB);
;     PG8_WAIT_V(6); PG8_BAR;
.LBB0_925:
	s_add_u32 s28, s58, 0x33114000
	s_addc_u32 s29, s59, 0
	s_add_u32 s68, s58, 0x314000
	s_addc_u32 s69, s59, 0
	s_and_b32 s70, s0, 3
	s_lshl_b32 s71, s1, 6
	s_lshl_b32 s0, s1, 13
	s_lshl_b32 s72, s70, 5
	s_lshl_b32 s1, s70, 12
	s_add_u32 s4, s14, 0x8000
	s_addc_u32 s5, s15, 0
	s_add_i32 s73, s48, 0x18000
	s_and_b32 s5, s5, 0xffff
	s_mov_b32 m0, s73
	s_add_i32 s74, s48, 0x1a000
	buffer_load_dwordx4 v129, s[4:7], 0 offen lds
	s_mov_b32 m0, s74
	v_and_b32_e32 v1, 48, v0
	buffer_load_dwordx4 v131, s[4:7], 0 offen lds
	s_add_u32 s4, s12, 0x80
	s_addc_u32 s5, s13, 0
	s_add_i32 s75, s48, 0x8000
	s_and_b32 s5, s5, 0xffff
	s_mov_b32 m0, s75
	s_add_i32 s76, s48, 0xa000
	buffer_load_dwordx4 v128, s[4:7], 0 offen lds
	s_mov_b32 m0, s76
	v_lshlrev_b32_e32 v2, 6, v0
	buffer_load_dwordx4 v130, s[4:7], 0 offen lds
	s_add_u32 s4, s14, 0xc000
	s_addc_u32 s5, s15, 0
	s_add_i32 s77, s48, 0x1c000
	s_and_b32 s5, s5, 0xffff
	s_mov_b32 m0, s77
	s_add_i32 s78, s48, 0x1e000
	buffer_load_dwordx4 v129, s[4:7], 0 offen lds
	s_mov_b32 m0, s78
	v_lshlrev_b32_e32 v0, 2, v0
	buffer_load_dwordx4 v131, s[4:7], 0 offen lds
	s_movk_i32 s4, 0x3c0
	v_and_or_b32 v1, v2, s4, v1
	v_and_b32_e32 v0, 32, v0
	v_bitop3_b32 v2, v1, s0, v0 bitop3:0xde
	v_bitop3_b32 v0, v1, s1, v0 bitop3:0xde
	s_waitcnt vmcnt(8)
	s_barrier
	s_waitcnt vmcnt(6)
	s_add_i32 s79, s48, 0xc000
	s_cmpk_lt_u32 s16, 0x100
	v_readlane_b32 s0, v255, 0
	v_add_u32_e32 v0, 0, v0
	s_cselect_b64 s[30:31], -1, 0
	s_add_i32 s80, s48, 0xe000
	s_ashr_i32 s81, s0, 31
	s_mov_b32 s82, s0
	s_ashr_i32 s83, s2, 31
	v_mov_b64_e32 v[132:133], 0x200
	v_mov_b64_e32 v[134:135], 0x1ff
	v_add_u32_e32 v142, 0x10000, v0
	v_add_u32_e32 v143, 0x14000, v0
	v_add_u32_e32 v144, 0, v2
	v_add_u32_e32 v145, 0x18000, v0
	v_add_u32_e32 v146, 0x1c000, v0
	v_mbcnt_hi_u32_b32 v147, -1, v192
	s_mov_b64 s[36:37], 0x100000
	s_mov_b32 s33, 0x100000
	s_mov_b64 s[38:39], 0x120000
	s_mov_b32 s62, 0x120000
	s_mov_b64 s[40:41], 0x140000
	s_mov_b32 s63, 0x140000
	s_mov_b64 s[42:43], 0x160000
	s_mov_b32 s84, 0x160000
	s_mov_b64 s[44:45], s[12:13]
	s_mov_b64 s[46:47], s[14:15]
	s_barrier
	v_readlane_b32 s1, v255, 1
	s_branch .LBB0_928
